# MLA loop trims: no-rescale path branches straight to exp block, x+0 removed, per-lane partial row sums with one cross-half combine per unit
# speedup vs baseline: 1.0827x; 1.0112x over previous
; DI unsigned pk2(float lo, float hi) { f32x2 v = {lo, hi}; bf2_t r = __builtin_convertvector(v, bf2_t); return __builtin_bit_cast(unsigned, r); }
; DI float pl32_sum(float v) { auto rr = __builtin_amdgcn_permlane32_swap(__float_as_uint(v), __float_as_uint(v), false, false); return __uint_as_float(rr[0]) + __uint_as_float(rr[1]); }
; DI void mla_unit(const Params& p, char* lds, int seqbase, int S, int h, int qb) {
;     ...
;     ps = pl32_sum(ps);
;     l_run += ps;
;     ...
;   __builtin_amdgcn_s_setprio(0);
;   __syncthreads();
;     ...
;   const float inv = 1.f / l_run;
;   u16* oo = O + (size_t)qrow * 1024 + h * 64 + 4 * hi;
; #pragma unroll
;   for (int g = 0; g < 4; ++g) {
;     u32x2 w0 = {pk2(o0[4 * g] * inv, o0[4 * g + 1] * inv), pk2(o0[4 * g + 2] * inv, o0[4 * g + 3] * inv)};
;     u32x2 w1 = {pk2(o1[4 * g] * inv, o1[4 * g + 1] * inv), pk2(o1[4 * g + 2] * inv, o1[4 * g + 3] * inv)};
;     *(u32x2*)(oo + 8 * g) = w0; *(u32x2*)(oo + 32 + 8 * g) = w1;
;   }
.LBB0_1063:
	s_setprio 0
	v_mov_b32_e32 v14, v153
	s_nop 1
	v_permlane32_swap_b32_e32 v153, v14
	v_add_f32_e32 v153, v153, v14
	v_div_scale_f32 v0, s[28:29], v153, v153, 1.0
	v_rcp_f32_e32 v2, v0
	s_lshl_b32 s36, s62, 7
	s_waitcnt lgkmcnt(0)
	s_barrier
	v_fma_f32 v3, -v0, v2, 1.0
	v_fmac_f32_e32 v2, v3, v2
	v_div_scale_f32 v3, vcc, 1.0, v153, 1.0
	v_mul_f32_e32 v4, v3, v2
	v_fma_f32 v5, -v0, v4, v3
	v_fmac_f32_e32 v4, v5, v2
	v_fma_f32 v0, -v0, v4, v3
	v_div_fmas_f32 v0, v0, v2, v4
	v_div_fixup_f32 v2, v0, v153, 1.0
	v_lshlrev_b64 v[4:5], 11, v[168:169]
	v_lshl_add_u64 v[4:5], s[16:17], 0, v[4:5]
	v_pk_mul_f32 v[6:7], v[2:3], v[32:33] op_sel_hi:[0,1]
	v_pk_mul_f32 v[8:9], v[2:3], v[34:35] op_sel_hi:[0,1]
	v_lshl_add_u64 v[4:5], v[4:5], 0, s[36:37]
	v_lshlrev_b32_e32 v0, 1, v152
	v_cvt_pk_bf16_f32 v6, v6, v7
	v_cvt_pk_bf16_f32 v7, v8, v9
	v_pk_mul_f32 v[8:9], v[2:3], v[16:17] op_sel_hi:[0,1]
	v_pk_mul_f32 v[10:11], v[2:3], v[18:19] op_sel_hi:[0,1]
	v_lshl_add_u64 v[4:5], v[4:5], 0, v[0:1]
	v_cvt_pk_bf16_f32 v8, v8, v9
	v_cvt_pk_bf16_f32 v9, v10, v11
	global_store_dwordx2 v[4:5], v[6:7], off
	global_store_dwordx2 v[4:5], v[8:9], off offset:64
	v_pk_mul_f32 v[6:7], v[2:3], v[36:37] op_sel_hi:[0,1]
	v_pk_mul_f32 v[8:9], v[2:3], v[38:39] op_sel_hi:[0,1]
	v_cvt_pk_bf16_f32 v6, v6, v7
	v_cvt_pk_bf16_f32 v7, v8, v9
	v_pk_mul_f32 v[8:9], v[2:3], v[20:21] op_sel_hi:[0,1]
	v_pk_mul_f32 v[10:11], v[2:3], v[22:23] op_sel_hi:[0,1]
	v_cvt_pk_bf16_f32 v8, v8, v9
	v_cvt_pk_bf16_f32 v9, v10, v11
	global_store_dwordx2 v[4:5], v[6:7], off offset:16
	global_store_dwordx2 v[4:5], v[8:9], off offset:80
	v_pk_mul_f32 v[6:7], v[2:3], v[40:41] op_sel_hi:[0,1]
	v_pk_mul_f32 v[8:9], v[2:3], v[42:43] op_sel_hi:[0,1]
	v_cvt_pk_bf16_f32 v6, v6, v7
	v_cvt_pk_bf16_f32 v7, v8, v9
	v_pk_mul_f32 v[8:9], v[2:3], v[24:25] op_sel_hi:[0,1]
	v_pk_mul_f32 v[10:11], v[2:3], v[26:27] op_sel_hi:[0,1]
	v_cvt_pk_bf16_f32 v8, v8, v9
	v_cvt_pk_bf16_f32 v9, v10, v11
	global_store_dwordx2 v[4:5], v[6:7], off offset:32
	global_store_dwordx2 v[4:5], v[8:9], off offset:96
	v_pk_mul_f32 v[6:7], v[2:3], v[44:45] op_sel_hi:[0,1]
	v_pk_mul_f32 v[8:9], v[2:3], v[46:47] op_sel_hi:[0,1]
	v_cvt_pk_bf16_f32 v6, v6, v7
	v_cvt_pk_bf16_f32 v7, v8, v9
	v_pk_mul_f32 v[8:9], v[2:3], v[28:29] op_sel_hi:[0,1]
	v_pk_mul_f32 v[2:3], v[2:3], v[30:31] op_sel_hi:[0,1]
	s_add_i32 s61, s61, s56
	v_cvt_pk_bf16_f32 v8, v8, v9
	v_cvt_pk_bf16_f32 v9, v2, v3
	s_cmp_ge_i32 s61, s39
	global_store_dwordx2 v[4:5], v[6:7], off offset:48
	global_store_dwordx2 v[4:5], v[8:9], off offset:112
	s_cbranch_scc1 .LBB0_1092

; #define MFMA32(a, b, c) __builtin_amdgcn_mfma_f32_32x32x16_bf16((a), (b), (c), 0, 0, 0)
; #define LGKM0() do { asm volatile("s_waitcnt lgkmcnt(0)" ::: "memory"); __builtin_amdgcn_sched_barrier(0); } while (0)
; DI bf16x8 cat4(s16x4 l, s16x4 h) { return (bf16x8){l[0], l[1], l[2], l[3], h[0], h[1], h[2], h[3]}; }
; #define MLA_LSTORE(B) do { u16* kd = Kl + (B) * 64 * KP; u16* vd = Vl + (B) * 64 * VP; *(u32x4*)(kd + kdst0) = rkn; *(u32x4*)(vd + vdst) = rvv; \
;     if (kr_on) *(u32x4*)(kd + kdst2) = rkr; } while (0)
; DI void mla_unit(const Params& p, char* lds, int seqbase, int S, int h, int qb) {
;     ...
;     l_run += ps;
;     const bf16x8 pb0 = pack8(p0, 0), pb1 = pack8(p0, 1), pb2 = pack8(p1, 0), pb3 = pack8(p1, 1);
;     LGKM0();
;     o0 = MFMA32(cat4(a0, b0), pb0, o0); o1 = MFMA32(cat4(c0, d0_), pb0, o1);
;     o0 = MFMA32(cat4(a1, b1), pb1, o0); o1 = MFMA32(cat4(c1, d1), pb1, o1);
;     o0 = MFMA32(cat4(a2, b2), pb2, o0); o1 = MFMA32(cat4(c2, d2), pb2, o1);
;     o0 = MFMA32(cat4(a3, b3), pb3, o0); o1 = MFMA32(cat4(c3, d3), pb3, o1);
;     __syncthreads();
;     if (kt + 2 < nkt) MLA_LSTORE(nx2);
;     cur = cur == 2 ? 0 : cur + 1; nx2 = nx2 == 2 ? 0 : nx2 + 1;
.LBB0_1076:
	s_add_i32 s28, s36, 1
	s_cmp_lg_u32 s36, 2
	s_cselect_b32 s36, s28, 0
	s_add_i32 s28, s63, 1
	s_cmp_lg_u32 s63, 2
	s_cselect_b32 s63, s28, 0
	s_add_i32 s64, s64, 1
	s_add_u32 s46, s46, 0x42000
	s_addc_u32 s47, s47, 0
	v_add_f32_e32 v153, v153, v0
	s_cmp_lg_u32 s46, 0x2100000
	v_lshl_add_u64 v[170:171], v[170:171], 0, s[40:41]
	s_cbranch_scc0 .LBB0_1063

; #define MFMA32(a, b, c) __builtin_amdgcn_mfma_f32_32x32x16_bf16((a), (b), (c), 0, 0, 0)
; DI float pl32_sum(float v) { auto rr = __builtin_amdgcn_permlane32_swap(__float_as_uint(v), __float_as_uint(v), false, false); return __uint_as_float(rr[0]) + __uint_as_float(rr[1]); }
; #define LGKM0() do { asm volatile("s_waitcnt lgkmcnt(0)" ::: "memory"); __builtin_amdgcn_sched_barrier(0); } while (0)
; DI bf16x8 cat4(s16x4 l, s16x4 h) { return (bf16x8){l[0], l[1], l[2], l[3], h[0], h[1], h[2], h[3]}; }
; #define MLA_LSTORE(B) do { u16* kd = Kl + (B) * 64 * KP; u16* vd = Vl + (B) * 64 * VP; *(u32x4*)(kd + kdst0) = rkn; *(u32x4*)(vd + vdst) = rvv; \
;     if (kr_on) *(u32x4*)(kd + kdst2) = rkr; } while (0)
; DI void mla_unit(const Params& p, char* lds, int seqbase, int S, int h, int qb) {
;     ...
;     float ps = 0.f;
; #pragma unroll
;     for (int r = 0; r < 16; ++r) { p0[r] = __builtin_amdgcn_exp2f(p0[r]); p1[r] = __builtin_amdgcn_exp2f(p1[r]); ps += p0[r] + p1[r]; }
;     ps = pl32_sum(ps);
;     l_run += ps;
;     const bf16x8 pb0 = pack8(p0, 0), pb1 = pack8(p0, 1), pb2 = pack8(p1, 0), pb3 = pack8(p1, 1);
;     LGKM0();
;     o0 = MFMA32(cat4(a0, b0), pb0, o0); o1 = MFMA32(cat4(c0, d0_), pb0, o1);
;     o0 = MFMA32(cat4(a1, b1), pb1, o0); o1 = MFMA32(cat4(c1, d1), pb1, o1);
;     o0 = MFMA32(cat4(a2, b2), pb2, o0); o1 = MFMA32(cat4(c2, d2), pb2, o1);
;     o0 = MFMA32(cat4(a3, b3), pb3, o0); o1 = MFMA32(cat4(c3, d3), pb3, o1);
;     __syncthreads();
;     if (kt + 2 < nkt) MLA_LSTORE(nx2);
.LBB0_1088:
	v_exp_f32_e32 v15, v64
	v_exp_f32_e32 v80, v80
	v_exp_f32_e32 v64, v65
	v_exp_f32_e32 v81, v81
	v_exp_f32_e32 v65, v66
	v_exp_f32_e32 v82, v82
	v_exp_f32_e32 v66, v67
	v_exp_f32_e32 v83, v83
	v_add_f32_e32 v0, v80, v15
	v_exp_f32_e32 v67, v68
	v_exp_f32_e32 v84, v84
	v_add_f32_e32 v14, v81, v64
	v_exp_f32_e32 v68, v69
	v_exp_f32_e32 v85, v85
	v_add_f32_e32 v0, v14, v0
	v_add_f32_e32 v14, v82, v65
	v_exp_f32_e32 v69, v70
	v_exp_f32_e32 v86, v86
	v_add_f32_e32 v0, v14, v0
	v_add_f32_e32 v14, v83, v66
	v_exp_f32_e32 v70, v71
	v_exp_f32_e32 v87, v87
	v_add_f32_e32 v0, v14, v0
	v_add_f32_e32 v14, v84, v67
	v_exp_f32_e32 v71, v72
	v_exp_f32_e32 v88, v88
	v_add_f32_e32 v0, v14, v0
	v_add_f32_e32 v14, v85, v68
	v_exp_f32_e32 v72, v73
	v_exp_f32_e32 v89, v89
	v_add_f32_e32 v0, v14, v0
	v_add_f32_e32 v14, v86, v69
	v_exp_f32_e32 v73, v74
	v_exp_f32_e32 v90, v90
	v_add_f32_e32 v0, v14, v0
	v_add_f32_e32 v14, v87, v70
	v_exp_f32_e32 v74, v75
	v_exp_f32_e32 v91, v91
	v_add_f32_e32 v0, v14, v0
	v_add_f32_e32 v14, v88, v71
	v_exp_f32_e32 v75, v76
	v_exp_f32_e32 v92, v92
	v_add_f32_e32 v0, v14, v0
	v_add_f32_e32 v14, v89, v72
	v_exp_f32_e32 v76, v77
	v_exp_f32_e32 v93, v93
	v_add_f32_e32 v0, v14, v0
	v_add_f32_e32 v14, v90, v73
	v_exp_f32_e32 v77, v78
	v_exp_f32_e32 v94, v94
	v_add_f32_e32 v0, v14, v0
	v_add_f32_e32 v14, v91, v74
	v_exp_f32_e32 v78, v79
	v_exp_f32_e32 v79, v95
	v_add_f32_e32 v0, v14, v0
	v_add_f32_e32 v14, v92, v75
	v_add_f32_e32 v0, v14, v0
	v_add_f32_e32 v14, v93, v76
	v_add_f32_e32 v0, v14, v0
	v_add_f32_e32 v14, v94, v77
	v_add_f32_e32 v0, v14, v0
	v_add_f32_e32 v14, v79, v78
	v_add_f32_e32 v0, v14, v0
	s_waitcnt lgkmcnt(0)
	v_cvt_pk_bf16_f32 v64, v15, v64
	v_cvt_pk_bf16_f32 v65, v65, v66
	v_cvt_pk_bf16_f32 v66, v67, v68
	v_cvt_pk_bf16_f32 v67, v69, v70
	v_cvt_pk_bf16_f32 v68, v71, v72
	v_cvt_pk_bf16_f32 v69, v73, v74
	v_cvt_pk_bf16_f32 v70, v75, v76
	v_cvt_pk_bf16_f32 v71, v77, v78
	v_cvt_pk_bf16_f32 v72, v80, v81
	v_cvt_pk_bf16_f32 v73, v82, v83
	v_cvt_pk_bf16_f32 v74, v84, v85
	v_cvt_pk_bf16_f32 v75, v86, v87
	v_cvt_pk_bf16_f32 v76, v88, v89
	v_cvt_pk_bf16_f32 v77, v90, v91
	v_cvt_pk_bf16_f32 v78, v92, v93
	v_cvt_pk_bf16_f32 v79, v94, v79
	v_mfma_f32_32x32x16_bf16 v[32:47], v[144:147], v[64:67], v[32:47]
	s_andn2_b64 vcc, exec, s[48:49]
	s_barrier
	v_mfma_f32_32x32x16_bf16 v[16:31], v[148:151], v[64:67], v[16:31]
	v_mfma_f32_32x32x16_bf16 v[32:47], v[136:139], v[68:71], v[32:47]
	v_mfma_f32_32x32x16_bf16 v[16:31], v[140:143], v[68:71], v[16:31]
	v_mfma_f32_32x32x16_bf16 v[32:47], v[10:13], v[72:75], v[32:47]
	v_mfma_f32_32x32x16_bf16 v[16:31], v[132:135], v[72:75], v[16:31]
	v_mfma_f32_32x32x16_bf16 v[32:47], v[6:9], v[76:79], v[32:47]
	v_mfma_f32_32x32x16_bf16 v[16:31], v[2:5], v[76:79], v[16:31]
	s_cbranch_vccnz .LBB0_1076
	s_mul_i32 s50, s63, 0x3400
	s_mul_i32 s28, s63, 0x3000
	v_lshl_add_u32 v2, v178, 1, s50
	s_waitcnt vmcnt(1)
	ds_write_b128 v2, v[100:103]
	v_add_u32_e32 v2, s28, v180
	s_waitcnt vmcnt(0)
	ds_write_b128 v2, v[104:107] offset:39936
	s_and_saveexec_b64 s[48:49], s[0:1]
	s_cbranch_execz .LBB0_1075
	v_lshl_add_u32 v2, v183, 1, s50
	ds_write_b128 v2, v[96:99] offset:128
	s_branch .LBB0_1075

; DI unsigned pk2(float lo, float hi) { f32x2 v = {lo, hi}; bf2_t r = __builtin_convertvector(v, bf2_t); return __builtin_bit_cast(unsigned, r); }
; DI float pl32_sum(float v) { auto rr = __builtin_amdgcn_permlane32_swap(__float_as_uint(v), __float_as_uint(v), false, false); return __uint_as_float(rr[0]) + __uint_as_float(rr[1]); }
; DI void mla_unit(const Params& p, char* lds, int seqbase, int S, int h, int qb) {
;     ...
;     ps = pl32_sum(ps);
;     l_run += ps;
;     ...
;   __builtin_amdgcn_s_setprio(0);
;   __syncthreads();
;     ...
;   const float inv = 1.f / l_run;
;   u16* oo = O + (size_t)qrow * 1024 + h * 64 + 4 * hi;
; #pragma unroll
;   for (int g = 0; g < 4; ++g) {
;     u32x2 w0 = {pk2(o0[4 * g] * inv, o0[4 * g + 1] * inv), pk2(o0[4 * g + 2] * inv, o0[4 * g + 3] * inv)};
;     u32x2 w1 = {pk2(o1[4 * g] * inv, o1[4 * g + 1] * inv), pk2(o1[4 * g + 2] * inv, o1[4 * g + 3] * inv)};
;     *(u32x2*)(oo + 8 * g) = w0; *(u32x2*)(oo + 32 + 8 * g) = w1;
;   }
.LBB0_1093:
	s_setprio 0
	v_mov_b32_e32 v16, v1
	s_nop 1
	v_permlane32_swap_b32_e32 v1, v16
	v_add_f32_e32 v1, v1, v16
	v_div_scale_f32 v2, s[28:29], v1, v1, 1.0
	v_rcp_f32_e32 v4, v2
	s_lshl_b32 s18, s55, 7
	s_waitcnt lgkmcnt(0)
	s_barrier
	v_fma_f32 v5, -v2, v4, 1.0
	v_fmac_f32_e32 v4, v5, v4
	v_div_scale_f32 v5, vcc, 1.0, v1, 1.0
	v_mul_f32_e32 v6, v5, v4
	v_fma_f32 v7, -v2, v6, v5
	v_fmac_f32_e32 v6, v7, v4
	v_fma_f32 v2, -v2, v6, v5
	v_div_fmas_f32 v2, v2, v4, v6
	v_div_fixup_f32 v2, v2, v1, 1.0
	v_lshlrev_b64 v[4:5], 11, v[168:169]
	v_lshl_add_u64 v[4:5], s[16:17], 0, v[4:5]
	v_pk_mul_f32 v[6:7], v[2:3], v[34:35] op_sel_hi:[0,1]
	v_pk_mul_f32 v[8:9], v[2:3], v[36:37] op_sel_hi:[0,1]
	v_lshl_add_u64 v[4:5], v[4:5], 0, s[18:19]
	v_mov_b32_e32 v1, v3
	v_cvt_pk_bf16_f32 v6, v6, v7
	v_cvt_pk_bf16_f32 v7, v8, v9
	v_pk_mul_f32 v[8:9], v[2:3], v[18:19] op_sel_hi:[0,1]
	v_pk_mul_f32 v[10:11], v[2:3], v[20:21] op_sel_hi:[0,1]
	v_lshl_add_u64 v[4:5], v[4:5], 0, v[0:1]
	v_cvt_pk_bf16_f32 v8, v8, v9
	v_cvt_pk_bf16_f32 v9, v10, v11
	global_store_dwordx2 v[4:5], v[6:7], off
	global_store_dwordx2 v[4:5], v[8:9], off offset:64
	v_pk_mul_f32 v[6:7], v[2:3], v[38:39] op_sel_hi:[0,1]
	v_pk_mul_f32 v[8:9], v[2:3], v[40:41] op_sel_hi:[0,1]
	v_cvt_pk_bf16_f32 v6, v6, v7
	v_cvt_pk_bf16_f32 v7, v8, v9
	v_pk_mul_f32 v[8:9], v[2:3], v[22:23] op_sel_hi:[0,1]
	v_pk_mul_f32 v[10:11], v[2:3], v[24:25] op_sel_hi:[0,1]
	v_cvt_pk_bf16_f32 v8, v8, v9
	v_cvt_pk_bf16_f32 v9, v10, v11
	global_store_dwordx2 v[4:5], v[6:7], off offset:16
	global_store_dwordx2 v[4:5], v[8:9], off offset:80
	v_pk_mul_f32 v[6:7], v[2:3], v[42:43] op_sel_hi:[0,1]
	v_pk_mul_f32 v[8:9], v[2:3], v[44:45] op_sel_hi:[0,1]
	v_cvt_pk_bf16_f32 v6, v6, v7
	v_cvt_pk_bf16_f32 v7, v8, v9
	v_pk_mul_f32 v[8:9], v[2:3], v[26:27] op_sel_hi:[0,1]
	v_pk_mul_f32 v[10:11], v[2:3], v[28:29] op_sel_hi:[0,1]
	v_cvt_pk_bf16_f32 v8, v8, v9
	v_cvt_pk_bf16_f32 v9, v10, v11
	global_store_dwordx2 v[4:5], v[6:7], off offset:32
	global_store_dwordx2 v[4:5], v[8:9], off offset:96
	v_pk_mul_f32 v[6:7], v[2:3], v[46:47] op_sel_hi:[0,1]
	v_pk_mul_f32 v[8:9], v[2:3], v[48:49] op_sel_hi:[0,1]
	v_cvt_pk_bf16_f32 v6, v6, v7
	v_cvt_pk_bf16_f32 v7, v8, v9
	v_pk_mul_f32 v[8:9], v[2:3], v[30:31] op_sel_hi:[0,1]
	v_pk_mul_f32 v[10:11], v[2:3], v[32:33] op_sel_hi:[0,1]
	s_add_i32 s35, s35, s56
	v_cvt_pk_bf16_f32 v8, v8, v9
	v_cvt_pk_bf16_f32 v9, v10, v11
	s_cmp_lt_i32 s35, s52
	global_store_dwordx2 v[4:5], v[6:7], off offset:48
	global_store_dwordx2 v[4:5], v[8:9], off offset:112
	s_cbranch_scc0 .LBB0_1122

; #define MFMA32(a, b, c) __builtin_amdgcn_mfma_f32_32x32x16_bf16((a), (b), (c), 0, 0, 0)
; #define LGKM0() do { asm volatile("s_waitcnt lgkmcnt(0)" ::: "memory"); __builtin_amdgcn_sched_barrier(0); } while (0)
; DI bf16x8 cat4(s16x4 l, s16x4 h) { return (bf16x8){l[0], l[1], l[2], l[3], h[0], h[1], h[2], h[3]}; }
; #define MLA_LSTORE(B) do { u16* kd = Kl + (B) * 64 * KP; u16* vd = Vl + (B) * 64 * VP; *(u32x4*)(kd + kdst0) = rkn; *(u32x4*)(vd + vdst) = rvv; \
;     if (kr_on) *(u32x4*)(kd + kdst2) = rkr; } while (0)
; DI void mla_unit(const Params& p, char* lds, int seqbase, int S, int h, int qb) {
;     ...
;     l_run += ps;
;     const bf16x8 pb0 = pack8(p0, 0), pb1 = pack8(p0, 1), pb2 = pack8(p1, 0), pb3 = pack8(p1, 1);
;     LGKM0();
;     o0 = MFMA32(cat4(a0, b0), pb0, o0); o1 = MFMA32(cat4(c0, d0_), pb0, o1);
;     o0 = MFMA32(cat4(a1, b1), pb1, o0); o1 = MFMA32(cat4(c1, d1), pb1, o1);
;     o0 = MFMA32(cat4(a2, b2), pb2, o0); o1 = MFMA32(cat4(c2, d2), pb2, o1);
;     o0 = MFMA32(cat4(a3, b3), pb3, o0); o1 = MFMA32(cat4(c3, d3), pb3, o1);
;     __syncthreads();
;     if (kt + 2 < nkt) MLA_LSTORE(nx2);
;     cur = cur == 2 ? 0 : cur + 1; nx2 = nx2 == 2 ? 0 : nx2 + 1;
.LBB0_1106:
	s_add_i32 s28, s18, 1
	s_cmp_lg_u32 s18, 2
	s_cselect_b32 s18, s28, 0
	s_add_i32 s28, s58, 1
	s_cmp_lg_u32 s58, 2
	s_cselect_b32 s58, s28, 0
	s_add_i32 s59, s59, 1
	s_add_u32 s38, s38, 0x42000
	s_addc_u32 s39, s39, 0
	v_add_f32_e32 v1, v1, v2
	s_cmp_lg_u32 s38, 0x1080000
	v_lshl_add_u64 v[170:171], v[170:171], 0, s[36:37]
	s_cbranch_scc0 .LBB0_1093

; #define MFMA32(a, b, c) __builtin_amdgcn_mfma_f32_32x32x16_bf16((a), (b), (c), 0, 0, 0)
; DI float pl32_sum(float v) { auto rr = __builtin_amdgcn_permlane32_swap(__float_as_uint(v), __float_as_uint(v), false, false); return __uint_as_float(rr[0]) + __uint_as_float(rr[1]); }
; #define LGKM0() do { asm volatile("s_waitcnt lgkmcnt(0)" ::: "memory"); __builtin_amdgcn_sched_barrier(0); } while (0)
; DI bf16x8 cat4(s16x4 l, s16x4 h) { return (bf16x8){l[0], l[1], l[2], l[3], h[0], h[1], h[2], h[3]}; }
; #define MLA_LSTORE(B) do { u16* kd = Kl + (B) * 64 * KP; u16* vd = Vl + (B) * 64 * VP; *(u32x4*)(kd + kdst0) = rkn; *(u32x4*)(vd + vdst) = rvv; \
;     if (kr_on) *(u32x4*)(kd + kdst2) = rkr; } while (0)
; DI void mla_unit(const Params& p, char* lds, int seqbase, int S, int h, int qb) {
;     ...
;     float ps = 0.f;
; #pragma unroll
;     for (int r = 0; r < 16; ++r) { p0[r] = __builtin_amdgcn_exp2f(p0[r]); p1[r] = __builtin_amdgcn_exp2f(p1[r]); ps += p0[r] + p1[r]; }
;     ps = pl32_sum(ps);
;     l_run += ps;
;     const bf16x8 pb0 = pack8(p0, 0), pb1 = pack8(p0, 1), pb2 = pack8(p1, 0), pb3 = pack8(p1, 1);
;     LGKM0();
;     o0 = MFMA32(cat4(a0, b0), pb0, o0); o1 = MFMA32(cat4(c0, d0_), pb0, o1);
;     o0 = MFMA32(cat4(a1, b1), pb1, o0); o1 = MFMA32(cat4(c1, d1), pb1, o1);
;     o0 = MFMA32(cat4(a2, b2), pb2, o0); o1 = MFMA32(cat4(c2, d2), pb2, o1);
;     o0 = MFMA32(cat4(a3, b3), pb3, o0); o1 = MFMA32(cat4(c3, d3), pb3, o1);
;     __syncthreads();
;     if (kt + 2 < nkt) MLA_LSTORE(nx2);
.LBB0_1118:
	v_exp_f32_e32 v17, v66
	v_exp_f32_e32 v82, v82
	v_exp_f32_e32 v66, v67
	v_exp_f32_e32 v83, v83
	v_exp_f32_e32 v67, v68
	v_exp_f32_e32 v84, v84
	v_exp_f32_e32 v68, v69
	v_exp_f32_e32 v85, v85
	v_add_f32_e32 v2, v82, v17
	v_exp_f32_e32 v69, v70
	v_exp_f32_e32 v86, v86
	v_add_f32_e32 v16, v83, v66
	v_exp_f32_e32 v70, v71
	v_exp_f32_e32 v87, v87
	v_add_f32_e32 v2, v16, v2
	v_add_f32_e32 v16, v84, v67
	v_exp_f32_e32 v71, v72
	v_exp_f32_e32 v88, v88
	v_add_f32_e32 v2, v16, v2
	v_add_f32_e32 v16, v85, v68
	v_exp_f32_e32 v72, v73
	v_exp_f32_e32 v89, v89
	v_add_f32_e32 v2, v16, v2
	v_add_f32_e32 v16, v86, v69
	v_exp_f32_e32 v73, v74
	v_exp_f32_e32 v90, v90
	v_add_f32_e32 v2, v16, v2
	v_add_f32_e32 v16, v87, v70
	v_exp_f32_e32 v74, v75
	v_exp_f32_e32 v91, v91
	v_add_f32_e32 v2, v16, v2
	v_add_f32_e32 v16, v88, v71
	v_exp_f32_e32 v75, v76
	v_exp_f32_e32 v92, v92
	v_add_f32_e32 v2, v16, v2
	v_add_f32_e32 v16, v89, v72
	v_exp_f32_e32 v76, v77
	v_exp_f32_e32 v93, v93
	v_add_f32_e32 v2, v16, v2
	v_add_f32_e32 v16, v90, v73
	v_exp_f32_e32 v77, v78
	v_exp_f32_e32 v94, v94
	v_add_f32_e32 v2, v16, v2
	v_add_f32_e32 v16, v91, v74
	v_exp_f32_e32 v78, v79
	v_exp_f32_e32 v95, v95
	v_add_f32_e32 v2, v16, v2
	v_add_f32_e32 v16, v92, v75
	v_exp_f32_e32 v79, v80
	v_exp_f32_e32 v96, v96
	v_add_f32_e32 v2, v16, v2
	v_add_f32_e32 v16, v93, v76
	v_exp_f32_e32 v80, v81
	v_exp_f32_e32 v81, v97
	v_add_f32_e32 v2, v16, v2
	v_add_f32_e32 v16, v94, v77
	v_add_f32_e32 v2, v16, v2
	v_add_f32_e32 v16, v95, v78
	v_add_f32_e32 v2, v16, v2
	v_add_f32_e32 v16, v96, v79
	v_add_f32_e32 v2, v16, v2
	v_add_f32_e32 v16, v81, v80
	v_add_f32_e32 v2, v16, v2
	s_waitcnt lgkmcnt(0)
	v_cvt_pk_bf16_f32 v66, v17, v66
	v_cvt_pk_bf16_f32 v67, v67, v68
	v_cvt_pk_bf16_f32 v68, v69, v70
	v_cvt_pk_bf16_f32 v69, v71, v72
	v_cvt_pk_bf16_f32 v70, v73, v74
	v_cvt_pk_bf16_f32 v71, v75, v76
	v_cvt_pk_bf16_f32 v72, v77, v78
	v_cvt_pk_bf16_f32 v73, v79, v80
	v_cvt_pk_bf16_f32 v74, v82, v83
	v_cvt_pk_bf16_f32 v75, v84, v85
	v_cvt_pk_bf16_f32 v76, v86, v87
	v_cvt_pk_bf16_f32 v77, v88, v89
	v_cvt_pk_bf16_f32 v78, v90, v91
	v_cvt_pk_bf16_f32 v79, v92, v93
	v_cvt_pk_bf16_f32 v80, v94, v95
	v_cvt_pk_bf16_f32 v81, v96, v81
	v_mfma_f32_32x32x16_bf16 v[34:49], v[146:149], v[66:69], v[34:49]
	s_andn2_b64 vcc, exec, s[40:41]
	s_barrier
	v_mfma_f32_32x32x16_bf16 v[18:33], v[150:153], v[66:69], v[18:33]
	v_mfma_f32_32x32x16_bf16 v[34:49], v[138:141], v[70:73], v[34:49]
	v_mfma_f32_32x32x16_bf16 v[18:33], v[142:145], v[70:73], v[18:33]
	v_mfma_f32_32x32x16_bf16 v[34:49], v[12:15], v[74:77], v[34:49]
	v_mfma_f32_32x32x16_bf16 v[18:33], v[134:137], v[74:77], v[18:33]
	v_mfma_f32_32x32x16_bf16 v[34:49], v[8:11], v[78:81], v[34:49]
	v_mfma_f32_32x32x16_bf16 v[18:33], v[4:7], v[78:81], v[18:33]
	s_cbranch_vccnz .LBB0_1106
	s_mul_i32 s46, s58, 0x3400
	s_mul_i32 s28, s58, 0x3000
	v_lshl_add_u32 v4, v178, 1, s46
	s_waitcnt vmcnt(1)
	ds_write_b128 v4, v[102:105]
	v_add_u32_e32 v4, s28, v180
	s_waitcnt vmcnt(0)
	ds_write_b128 v4, v[106:109] offset:39936
	s_and_saveexec_b64 s[40:41], s[0:1]
	s_cbranch_execz .LBB0_1105
	v_lshl_add_u32 v4, v183, 1, s46
	ds_write_b128 v4, v[98:101] offset:128
	s_branch .LBB0_1105
